# phase E: s_setprio 1 for the G3 items only (the phase's long pole; co-resident GEMM/head-norm blocks have slack)
# speedup vs baseline: 1.0040x; 1.0040x over previous
.LBB0_134:
	v_and_b32_e32 v33, 64, v212
	v_xor_b32_e32 v32, 1, v212
	v_add_u32_e32 v33, 64, v33
	v_cmp_lt_i32_e32 vcc, v32, v33
	v_lshlrev_b32_e32 v42, 16, v108
	s_lshl_b32 s0, s28, 1
	v_cndmask_b32_e32 v32, v212, v32, vcc
	v_lshlrev_b32_e32 v60, 2, v32
	v_xor_b32_e32 v32, 2, v212
	v_cmp_lt_i32_e32 vcc, v32, v33
	v_readlane_b32 s1, v252, 59
	s_add_u32 s0, s1, s0
	v_cndmask_b32_e32 v32, v212, v32, vcc
	v_lshlrev_b32_e32 v58, 2, v32
	v_xor_b32_e32 v32, 4, v212
	v_cmp_lt_i32_e32 vcc, v32, v33
	v_readlane_b32 s1, v252, 60
	s_addc_u32 s1, s1, 0
	v_cndmask_b32_e32 v32, v212, v32, vcc
	v_lshlrev_b32_e32 v47, 2, v32
	v_xor_b32_e32 v32, 8, v212
	v_cmp_lt_i32_e32 vcc, v32, v33
	v_mov_b32_e32 v33, v24
	s_movk_i32 s24, 0xc00
	v_cndmask_b32_e32 v32, v212, v32, vcc
	v_lshlrev_b32_e32 v46, 2, v32
	v_mov_b32_e32 v32, v12
	v_pk_mul_f32 v[36:37], v[32:33], v[32:33]
	v_mov_b32_e32 v32, v20
	v_mov_b32_e32 v33, v4
	v_pk_mul_f32 v[34:35], v[32:33], v[32:33]
	v_mul_f32_e32 v33, 0xbfb8aa3b, v42
	v_exp_f32_e32 v38, v33
	v_mov_b32_e32 v32, v0
	v_mov_b32_e32 v33, v8
	v_pk_mul_f32 v[40:41], v[32:33], v[32:33]
	v_add_f32_e32 v44, 1.0, v38
	v_mov_b64_e32 v[32:33], s[0:1]
	v_div_scale_f32 v45, s[0:1], v44, v44, 1.0
	v_rcp_f32_e32 v61, v45
	v_mad_i64_i32 v[38:39], s[0:1], v56, s24, v[32:33]
	v_lshlrev_b32_e32 v63, 2, v54
	v_fma_f32 v56, -v45, v61, 1.0
	v_fmac_f32_e32 v61, v56, v61
	v_div_scale_f32 v56, vcc, 1.0, v44, 1.0
	v_mul_f32_e32 v62, v56, v61
	v_fma_f32 v64, -v45, v62, v56
	v_fmac_f32_e32 v62, v64, v61
	v_fma_f32 v45, -v45, v62, v56
	v_lshlrev_b32_e32 v56, 16, v107
	v_mul_f32_e32 v64, 0xbfb8aa3b, v56
	v_exp_f32_e32 v64, v64
	v_div_fmas_f32 v45, v45, v61, v62
	v_div_fixup_f32 v44, v45, v44, 1.0
	v_lshlrev_b32_e32 v128, 1, v54
	v_add_f32_e32 v45, 1.0, v64
	v_div_scale_f32 v61, s[0:1], v45, v45, 1.0
	v_rcp_f32_e32 v62, v61
	v_lshlrev_b32_e32 v54, 16, v106
	v_mul_f32_e32 v74, v44, v42
	v_mul_f32_e32 v64, 0xbfb8aa3b, v54
	v_fma_f32 v42, -v61, v62, 1.0
	v_fmac_f32_e32 v62, v42, v62
	v_div_scale_f32 v42, vcc, 1.0, v45, 1.0
	v_exp_f32_e32 v64, v64
	v_mul_f32_e32 v44, v42, v62
	v_fma_f32 v65, -v61, v44, v42
	v_fmac_f32_e32 v44, v65, v62
	v_fma_f32 v42, -v61, v44, v42
	v_add_f32_e32 v61, 1.0, v64
	v_div_scale_f32 v64, s[0:1], v61, v61, 1.0
	v_rcp_f32_e32 v65, v64
	v_div_fmas_f32 v42, v42, v62, v44
	v_div_fixup_f32 v42, v42, v45, 1.0
	v_lshlrev_b32_e32 v45, 16, v105
	v_mul_f32_e32 v75, v42, v56
	v_mul_f32_e32 v56, 0xbfb8aa3b, v45
	v_fma_f32 v42, -v64, v65, 1.0
	v_exp_f32_e32 v56, v56
	v_fmac_f32_e32 v65, v42, v65
	v_div_scale_f32 v42, vcc, 1.0, v61, 1.0
	v_mul_f32_e32 v44, v42, v65
	v_fma_f32 v62, -v64, v44, v42
	v_fmac_f32_e32 v44, v62, v65
	v_add_f32_e32 v56, 1.0, v56
	v_fma_f32 v42, -v64, v44, v42
	v_div_scale_f32 v62, s[0:1], v56, v56, 1.0
	v_rcp_f32_e32 v64, v62
	v_div_fmas_f32 v42, v42, v65, v44
	v_div_fixup_f32 v42, v42, v61, 1.0
	v_mul_f32_e32 v76, v42, v54
	v_lshlrev_b32_e32 v54, 16, v104
	v_mul_f32_e32 v61, 0xbfb8aa3b, v54
	v_fma_f32 v42, -v62, v64, 1.0
	v_exp_f32_e32 v61, v61
	v_fmac_f32_e32 v64, v42, v64
	v_div_scale_f32 v42, vcc, 1.0, v56, 1.0
	v_mul_f32_e32 v44, v42, v64
	v_fma_f32 v65, -v62, v44, v42
	v_fmac_f32_e32 v44, v65, v64
	v_add_f32_e32 v61, 1.0, v61
	v_fma_f32 v42, -v62, v44, v42
	v_div_scale_f32 v62, s[0:1], v61, v61, 1.0
	v_rcp_f32_e32 v65, v62
	v_div_fmas_f32 v42, v42, v64, v44
	v_div_fixup_f32 v42, v42, v56, 1.0
	v_mul_f32_e32 v77, v42, v45
	v_lshlrev_b32_e32 v45, 16, v103
	v_fma_f32 v42, -v62, v65, 1.0
	v_mul_f32_e32 v56, 0xbfb8aa3b, v45
	v_fmac_f32_e32 v65, v42, v65
	v_div_scale_f32 v42, vcc, 1.0, v61, 1.0
	v_exp_f32_e32 v56, v56
	v_mul_f32_e32 v44, v42, v65
	v_fma_f32 v64, -v62, v44, v42
	v_fmac_f32_e32 v44, v64, v65
	v_fma_f32 v42, -v62, v44, v42
	v_add_f32_e32 v56, 1.0, v56
	v_div_scale_f32 v62, s[0:1], v56, v56, 1.0
	v_div_fmas_f32 v42, v42, v65, v44
	v_rcp_f32_e32 v64, v62
	v_div_fixup_f32 v42, v42, v61, 1.0
	v_lshlrev_b32_e32 v102, 16, v102
	v_mul_f32_e32 v103, v42, v54
	v_mul_f32_e32 v54, 0xbfb8aa3b, v102
	v_exp_f32_e32 v54, v54
	v_fma_f32 v42, -v62, v64, 1.0
	v_fmac_f32_e32 v64, v42, v64
	v_div_scale_f32 v42, vcc, 1.0, v56, 1.0
	v_mul_f32_e32 v44, v42, v64
	v_add_f32_e32 v104, 1.0, v54
	v_fma_f32 v61, -v62, v44, v42
	v_div_scale_f32 v54, s[0:1], v104, v104, 1.0
	v_fmac_f32_e32 v44, v61, v64
	v_rcp_f32_e32 v61, v54
	v_fma_f32 v42, -v62, v44, v42
	v_div_fmas_f32 v42, v42, v64, v44
	v_div_fixup_f32 v42, v42, v56, 1.0
	v_mul_f32_e32 v105, v42, v45
	v_fma_f32 v42, -v54, v61, 1.0
	v_fmac_f32_e32 v61, v42, v61
	v_div_scale_f32 v42, vcc, 1.0, v104, 1.0
	v_mul_f32_e32 v44, v42, v61
	v_fma_f32 v45, -v54, v44, v42
	v_readlane_b32 s30, v255, 52
	v_fmac_f32_e32 v44, v45, v61
	v_readlane_b32 s31, v255, 53
	v_fma_f32 v42, -v54, v44, v42
	v_div_fmas_f32 v106, v42, v61, v44
	v_mov_b32_e32 v64, v13
	v_mov_b32_e32 v65, v25
	v_pk_mul_f32 v[64:65], v[64:65], v[64:65]
	global_load_dword v43, v63, s[30:31]
	global_load_dword v62, v63, s[30:31] offset:64
	global_load_dword v61, v63, s[30:31] offset:128
	global_load_dword v56, v63, s[30:31] offset:192
	global_load_dword v54, v63, s[30:31] offset:256
	global_load_dword v45, v63, s[30:31] offset:320
	global_load_dword v44, v63, s[30:31] offset:384
	global_load_dword v42, v63, s[30:31] offset:448
	v_pk_mul_f32 v[66:67], v[16:17], v[16:17]
	v_mov_b32_e32 v68, v21
	v_pk_fma_f32 v[66:67], v[28:29], v[28:29], v[66:67]
	v_mov_b32_e32 v69, v5
	v_mov_b32_e32 v72, v64
	v_mov_b32_e32 v73, v36
	v_pk_mul_f32 v[68:69], v[68:69], v[68:69]
	v_pk_add_f32 v[66:67], v[66:67], v[72:73] op_sel:[1,0] op_sel_hi:[0,1]
	v_mov_b32_e32 v36, v65
	v_mov_b32_e32 v70, v1
	v_mov_b32_e32 v71, v9
	v_pk_add_f32 v[36:37], v[66:67], v[36:37]
	v_mov_b32_e32 v64, v68
	v_mov_b32_e32 v65, v34
	v_pk_mul_f32 v[70:71], v[70:71], v[70:71]
	v_pk_add_f32 v[36:37], v[36:37], v[64:65]
	v_mov_b32_e32 v34, v69
	v_pk_add_f32 v[34:35], v[36:37], v[34:35]
	v_mov_b32_e32 v36, v70
	v_mov_b32_e32 v37, v40
	v_pk_add_f32 v[34:35], v[34:35], v[36:37]
	v_mov_b32_e32 v40, v71
	v_pk_add_f32 v[34:35], v[34:35], v[40:41]
	ds_bpermute_b32 v37, v60, v35
	ds_bpermute_b32 v36, v60, v34
	v_lshlrev_b32_e32 v101, 16, v101
	v_mul_f32_e32 v63, 0xbfb8aa3b, v101
	v_exp_f32_e32 v63, v63
	s_brev_b32 s26, 60
	s_waitcnt lgkmcnt(0)
	v_pk_add_f32 v[34:35], v[34:35], v[36:37]
	ds_bpermute_b32 v37, v58, v35
	ds_bpermute_b32 v36, v58, v34
	v_add_f32_e32 v40, 1.0, v63
	v_div_scale_f32 v41, s[0:1], v40, v40, 1.0
	v_rcp_f32_e32 v63, v41
	s_waitcnt lgkmcnt(0)
	v_pk_add_f32 v[34:35], v[34:35], v[36:37]
	ds_bpermute_b32 v37, v47, v35
	ds_bpermute_b32 v36, v47, v34
	v_fma_f32 v65, -v41, v63, 1.0
	v_fmac_f32_e32 v63, v65, v63
	v_div_scale_f32 v65, vcc, 1.0, v40, 1.0
	s_waitcnt lgkmcnt(0)
	v_pk_add_f32 v[34:35], v[34:35], v[36:37]
	ds_bpermute_b32 v37, v46, v35
	ds_bpermute_b32 v36, v46, v34
	v_mul_f32_e32 v66, v65, v63
	v_fma_f32 v67, -v41, v66, v65
	v_fmac_f32_e32 v66, v67, v63
	v_fma_f32 v41, -v41, v66, v65
	s_mov_b32 s0, 0x358637bd
	v_div_fmas_f32 v41, v41, v63, v66
	s_waitcnt lgkmcnt(0)
	v_pk_add_f32 v[36:37], v[34:35], v[36:37]
	v_mov_b64_e32 v[34:35], s[0:1]
	v_div_fixup_f32 v63, v41, v40, 1.0
	v_pk_fma_f32 v[40:41], v[36:37], s[26:27], v[34:35] op_sel_hi:[1,0,0]
	v_lshl_add_u64 v[38:39], v[38:39], 0, v[128:129]
	v_mul_f32_e32 v36, 0x4b800000, v41
	v_cmp_gt_f32_e32 vcc, s3, v41
	v_div_fixup_f32 v64, v106, v104, 1.0
	v_mul_f32_e32 v64, v64, v102
	v_cndmask_b32_e32 v36, v41, v36, vcc
	v_rsq_f32_e32 v41, v36
	v_mul_f32_e32 v63, v63, v101
	v_pk_mul_f32 v[36:37], v[18:19], v[18:19]
	v_readlane_b32 s76, v255, 33
	v_mul_f32_e32 v65, 0x45800000, v41
	v_cndmask_b32_e32 v41, v41, v65, vcc
	v_mul_f32_e32 v12, v12, v41
	v_mul_f32_e32 v4, v4, v41
	v_mul_f32_e32 v0, v0, v41
	v_cmp_gt_f32_e32 vcc, s3, v40
	v_mul_f32_e32 v28, v28, v41
	v_mul_f32_e32 v16, v16, v41
	s_waitcnt vmcnt(5)
	v_mul_f32_e32 v12, v61, v12
	v_mul_f32_e32 v12, v76, v12
	v_cvt_pk_bf16_f32 v12, v12, s0
	global_store_short v[38:39], v12, off offset:64
	v_mul_f32_e32 v12, v24, v41
	s_waitcnt vmcnt(5)
	v_mul_f32_e32 v12, v56, v12
	v_mul_f32_e32 v12, v77, v12
	v_cvt_pk_bf16_f32 v12, v12, s0
	s_waitcnt vmcnt(3)
	v_mul_f32_e32 v4, v4, v45
	global_store_short v[38:39], v12, off offset:96
	v_mul_f32_e32 v12, v20, v41
	v_mul_f32_e32 v4, v105, v4
	s_waitcnt vmcnt(3)
	v_mul_f32_e32 v0, v0, v44
	v_mul_f32_e32 v12, v54, v12
	v_cvt_pk_bf16_f32 v4, v4, s0
	v_mul_f32_e32 v0, v64, v0
	v_mul_f32_e32 v12, v103, v12
	global_store_short v[38:39], v4, off offset:160
	v_cvt_pk_bf16_f32 v0, v0, s0
	v_mul_f32_e32 v4, 0x4b800000, v40
	v_cvt_pk_bf16_f32 v12, v12, s0
	global_store_short v[38:39], v0, off offset:192
	v_mul_f32_e32 v0, v8, v41
	v_cndmask_b32_e32 v4, v40, v4, vcc
	v_lshlrev_b32_e32 v8, 16, v100
	global_store_short v[38:39], v12, off offset:128
	v_rsq_f32_e32 v4, v4
	v_mul_f32_e32 v12, 0xbfb8aa3b, v8
	s_waitcnt vmcnt(5)
	v_mul_f32_e32 v0, v0, v42
	v_exp_f32_e32 v12, v12
	v_mul_f32_e32 v0, v63, v0
	v_cvt_pk_bf16_f32 v0, v0, s0
	v_mul_f32_e32 v28, v43, v28
	v_mul_f32_e32 v16, v62, v16
	global_store_short v[38:39], v0, off offset:224
	v_mul_f32_e32 v0, 0x45800000, v4
	v_mul_f32_e32 v28, v74, v28
	v_mul_f32_e32 v16, v75, v16
	v_cndmask_b32_e32 v0, v4, v0, vcc
	v_add_f32_e32 v4, 1.0, v12
	v_cvt_pk_bf16_f32 v28, v28, s0
	v_cvt_pk_bf16_f32 v16, v16, s0
	v_div_scale_f32 v12, s[0:1], v4, v4, 1.0
	global_store_short v[38:39], v16, off offset:32
	v_rcp_f32_e32 v16, v12
	global_store_short v[38:39], v28, off
	v_mul_f32_e32 v20, v29, v0
	v_mul_f32_e32 v20, v43, v20
	v_fma_f32 v24, -v12, v16, 1.0
	v_fmac_f32_e32 v16, v24, v16
	v_div_scale_f32 v24, vcc, 1.0, v4, 1.0
	v_mul_f32_e32 v28, v24, v16
	v_fma_f32 v29, -v12, v28, v24
	v_fmac_f32_e32 v28, v29, v16
	v_fma_f32 v12, -v12, v28, v24
	v_div_fmas_f32 v12, v12, v16, v28
	v_div_fixup_f32 v4, v12, v4, 1.0
	v_mul_f32_e32 v4, v4, v8
	v_lshlrev_b32_e32 v8, 16, v99
	v_mul_f32_e32 v12, 0xbfb8aa3b, v8
	v_exp_f32_e32 v12, v12
	v_mad_i64_i32 v[38:39], s[0:1], v52, s24, v[32:33]
	v_mul_f32_e32 v4, v4, v20
	v_add_f32_e32 v12, 1.0, v12
	v_cvt_pk_bf16_f32 v4, v4, s0
	v_div_scale_f32 v16, s[0:1], v12, v12, 1.0
	v_rcp_f32_e32 v20, v16
	v_lshl_add_u64 v[28:29], v[38:39], 0, v[128:129]
	global_store_short v[28:29], v4, off
	v_mul_f32_e32 v4, v17, v0
	v_fma_f32 v17, -v16, v20, 1.0
	v_fmac_f32_e32 v20, v17, v20
	v_div_scale_f32 v17, vcc, 1.0, v12, 1.0
	v_mul_f32_e32 v24, v17, v20
	v_fma_f32 v38, -v16, v24, v17
	v_fmac_f32_e32 v24, v38, v20
	v_fma_f32 v16, -v16, v24, v17
	v_div_fmas_f32 v16, v16, v20, v24
	v_div_fixup_f32 v12, v16, v12, 1.0
	v_lshlrev_b32_e32 v16, 16, v98
	v_mul_f32_e32 v17, 0xbfb8aa3b, v16
	v_exp_f32_e32 v17, v17
	v_mul_f32_e32 v4, v62, v4
	v_mul_f32_e32 v8, v12, v8
	v_mul_f32_e32 v4, v8, v4
	v_add_f32_e32 v8, 1.0, v17
	v_cvt_pk_bf16_f32 v4, v4, s0
	v_div_scale_f32 v12, s[0:1], v8, v8, 1.0
	v_rcp_f32_e32 v17, v12
	global_store_short v[28:29], v4, off offset:32
	v_mul_f32_e32 v4, v13, v0
	v_mul_f32_e32 v4, v61, v4
	v_fma_f32 v13, -v12, v17, 1.0
	v_fmac_f32_e32 v17, v13, v17
	v_div_scale_f32 v13, vcc, 1.0, v8, 1.0
	v_mul_f32_e32 v20, v13, v17
	v_fma_f32 v24, -v12, v20, v13
	v_fmac_f32_e32 v20, v24, v17
	v_fma_f32 v12, -v12, v20, v13
	v_div_fmas_f32 v12, v12, v17, v20
	v_div_fixup_f32 v8, v12, v8, 1.0
	v_lshlrev_b32_e32 v12, 16, v97
	v_mul_f32_e32 v13, 0xbfb8aa3b, v12
	v_exp_f32_e32 v13, v13
	v_mul_f32_e32 v8, v8, v16
	v_mul_f32_e32 v4, v8, v4
	v_cvt_pk_bf16_f32 v4, v4, s0
	v_add_f32_e32 v8, 1.0, v13
	v_div_scale_f32 v13, s[0:1], v8, v8, 1.0
	v_rcp_f32_e32 v16, v13
	global_store_short v[28:29], v4, off offset:64
	v_mul_f32_e32 v4, v25, v0
	v_mul_f32_e32 v4, v56, v4
	v_fma_f32 v17, -v13, v16, 1.0
	v_fmac_f32_e32 v16, v17, v16
	v_div_scale_f32 v17, vcc, 1.0, v8, 1.0
	v_mul_f32_e32 v20, v17, v16
	v_fma_f32 v24, -v13, v20, v17
	v_fmac_f32_e32 v20, v24, v16
	v_fma_f32 v13, -v13, v20, v17
	v_div_fmas_f32 v13, v13, v16, v20
	v_div_fixup_f32 v8, v13, v8, 1.0
	v_lshlrev_b32_e32 v13, 16, v96
	v_mul_f32_e32 v16, 0xbfb8aa3b, v13
	v_exp_f32_e32 v16, v16
	v_mul_f32_e32 v8, v8, v12
	v_mul_f32_e32 v4, v8, v4
	v_cvt_pk_bf16_f32 v4, v4, s0
	v_add_f32_e32 v8, 1.0, v16
	v_div_scale_f32 v12, s[0:1], v8, v8, 1.0
	v_rcp_f32_e32 v16, v12
	global_store_short v[28:29], v4, off offset:96
	v_mul_f32_e32 v4, v21, v0
	v_mul_f32_e32 v4, v54, v4
	v_fma_f32 v17, -v12, v16, 1.0
	v_fmac_f32_e32 v16, v17, v16
	v_div_scale_f32 v17, vcc, 1.0, v8, 1.0
	v_mul_f32_e32 v20, v17, v16
	v_fma_f32 v21, -v12, v20, v17
	v_fmac_f32_e32 v20, v21, v16
	v_fma_f32 v12, -v12, v20, v17
	v_div_fmas_f32 v12, v12, v16, v20
	v_div_fixup_f32 v8, v12, v8, 1.0
	v_lshlrev_b32_e32 v12, 16, v95
	v_mul_f32_e32 v16, 0xbfb8aa3b, v12
	v_exp_f32_e32 v16, v16
	v_mul_f32_e32 v8, v8, v13
	v_mul_f32_e32 v4, v8, v4
	v_cvt_pk_bf16_f32 v4, v4, s0
	v_add_f32_e32 v8, 1.0, v16
	v_div_scale_f32 v13, s[0:1], v8, v8, 1.0
	v_rcp_f32_e32 v16, v13
	global_store_short v[28:29], v4, off offset:128
	v_mul_f32_e32 v4, v5, v0
	v_mul_f32_e32 v4, v45, v4
	v_fma_f32 v5, -v13, v16, 1.0
	v_fmac_f32_e32 v16, v5, v16
	v_div_scale_f32 v5, vcc, 1.0, v8, 1.0
	v_mul_f32_e32 v17, v5, v16
	v_fma_f32 v20, -v13, v17, v5
	v_fmac_f32_e32 v17, v20, v16
	v_fma_f32 v5, -v13, v17, v5
	v_div_fmas_f32 v5, v5, v16, v17
	v_div_fixup_f32 v5, v5, v8, 1.0
	v_lshlrev_b32_e32 v8, 16, v94
	v_mul_f32_e32 v13, 0xbfb8aa3b, v8
	v_exp_f32_e32 v13, v13
	v_mul_f32_e32 v5, v5, v12
	v_mul_f32_e32 v4, v5, v4
	v_cvt_pk_bf16_f32 v4, v4, s0
	v_add_f32_e32 v5, 1.0, v13
	v_div_scale_f32 v12, s[0:1], v5, v5, 1.0
	v_rcp_f32_e32 v13, v12
	global_store_short v[28:29], v4, off offset:160
	v_mul_f32_e32 v1, v1, v0
	v_mul_f32_e32 v1, v44, v1
	v_fma_f32 v4, -v12, v13, 1.0
	v_fmac_f32_e32 v13, v4, v13
	v_div_scale_f32 v4, vcc, 1.0, v5, 1.0
	v_mul_f32_e32 v16, v4, v13
	v_fma_f32 v17, -v12, v16, v4
	v_fmac_f32_e32 v16, v17, v13
	v_fma_f32 v4, -v12, v16, v4
	v_div_fmas_f32 v4, v4, v13, v16
	v_div_fixup_f32 v4, v4, v5, 1.0
	v_lshlrev_b32_e32 v5, 16, v93
	v_mul_f32_e32 v12, 0xbfb8aa3b, v5
	v_exp_f32_e32 v12, v12
	v_mul_f32_e32 v4, v4, v8
	v_mul_f32_e32 v1, v4, v1
	v_cvt_pk_bf16_f32 v1, v1, s0
	v_add_f32_e32 v4, 1.0, v12
	v_div_scale_f32 v8, s[0:1], v4, v4, 1.0
	v_rcp_f32_e32 v12, v8
	global_store_short v[28:29], v1, off offset:192
	v_mul_f32_e32 v0, v9, v0
	v_lshlrev_b32_e32 v16, 16, v92
	v_fma_f32 v1, -v8, v12, 1.0
	v_fmac_f32_e32 v12, v1, v12
	v_div_scale_f32 v1, vcc, 1.0, v4, 1.0
	v_mul_f32_e32 v9, v1, v12
	v_fma_f32 v13, -v8, v9, v1
	v_fmac_f32_e32 v9, v13, v12
	v_fma_f32 v1, -v8, v9, v1
	v_mul_f32_e32 v8, 0xbfb8aa3b, v16
	v_div_fmas_f32 v1, v1, v12, v9
	v_exp_f32_e32 v12, v8
	v_div_fixup_f32 v1, v1, v4, 1.0
	v_mul_f32_e32 v0, v42, v0
	v_mul_f32_e32 v1, v1, v5
	v_mul_f32_e32 v0, v1, v0
	v_add_f32_e32 v17, 1.0, v12
	v_cvt_pk_bf16_f32 v0, v0, s0
	v_div_scale_f32 v20, s[0:1], v17, v17, 1.0
	v_rcp_f32_e32 v21, v20
	global_store_short v[28:29], v0, off offset:224
	v_mov_b32_e32 v0, v14
	v_mov_b32_e32 v1, v26
	v_fma_f32 v24, -v20, v21, 1.0
	v_fmac_f32_e32 v21, v24, v21
	v_div_scale_f32 v24, vcc, 1.0, v17, 1.0
	v_mul_f32_e32 v25, v24, v21
	v_fma_f32 v28, -v20, v25, v24
	v_fmac_f32_e32 v25, v28, v21
	v_lshlrev_b32_e32 v28, 16, v91
	v_mul_f32_e32 v29, 0xbfb8aa3b, v28
	v_exp_f32_e32 v29, v29
	v_fma_f32 v20, -v20, v25, v24
	v_div_fmas_f32 v20, v20, v21, v25
	v_div_fixup_f32 v17, v20, v17, 1.0
	v_add_f32_e32 v21, 1.0, v29
	v_div_scale_f32 v24, s[0:1], v21, v21, 1.0
	v_rcp_f32_e32 v25, v24
	v_lshlrev_b32_e32 v20, 16, v90
	v_mul_f32_e32 v38, v17, v16
	v_mul_f32_e32 v29, 0xbfb8aa3b, v20
	v_fma_f32 v16, -v24, v25, 1.0
	v_fmac_f32_e32 v25, v16, v25
	v_div_scale_f32 v16, vcc, 1.0, v21, 1.0
	v_exp_f32_e32 v29, v29
	v_mul_f32_e32 v17, v16, v25
	v_fma_f32 v39, -v24, v17, v16
	v_fmac_f32_e32 v17, v39, v25
	v_fma_f32 v16, -v24, v17, v16
	v_add_f32_e32 v24, 1.0, v29
	v_div_scale_f32 v29, s[0:1], v24, v24, 1.0
	v_rcp_f32_e32 v39, v29
	v_div_fmas_f32 v16, v16, v25, v17
	v_div_fixup_f32 v16, v16, v21, 1.0
	v_lshlrev_b32_e32 v21, 16, v89
	v_mul_f32_e32 v25, 0xbfb8aa3b, v21
	v_mul_f32_e32 v40, v16, v28
	v_fma_f32 v16, -v29, v39, 1.0
	v_exp_f32_e32 v25, v25
	v_fmac_f32_e32 v39, v16, v39
	v_div_scale_f32 v16, vcc, 1.0, v24, 1.0
	v_mul_f32_e32 v17, v16, v39
	v_fma_f32 v28, -v29, v17, v16
	v_fmac_f32_e32 v17, v28, v39
	v_add_f32_e32 v25, 1.0, v25
	v_fma_f32 v16, -v29, v17, v16
	v_div_scale_f32 v28, s[0:1], v25, v25, 1.0
	v_rcp_f32_e32 v29, v28
	v_div_fmas_f32 v16, v16, v39, v17
	v_div_fixup_f32 v16, v16, v24, 1.0
	v_mul_f32_e32 v39, v16, v20
	v_lshlrev_b32_e32 v20, 16, v88
	v_mul_f32_e32 v24, 0xbfb8aa3b, v20
	v_fma_f32 v16, -v28, v29, 1.0
	v_exp_f32_e32 v24, v24
	v_fmac_f32_e32 v29, v16, v29
	v_div_scale_f32 v16, vcc, 1.0, v25, 1.0
	v_mul_f32_e32 v17, v16, v29
	v_fma_f32 v41, -v28, v17, v16
	v_fmac_f32_e32 v17, v41, v29
	v_add_f32_e32 v24, 1.0, v24
	v_fma_f32 v16, -v28, v17, v16
	v_div_scale_f32 v28, s[0:1], v24, v24, 1.0
	v_pk_mul_f32 v[4:5], v[0:1], v[0:1]
	v_mov_b32_e32 v0, v22
	v_mov_b32_e32 v1, v6
	v_rcp_f32_e32 v41, v28
	v_div_fmas_f32 v16, v16, v29, v17
	v_pk_mul_f32 v[8:9], v[0:1], v[0:1]
	v_mov_b32_e32 v0, v2
	v_mov_b32_e32 v1, v10
	v_div_fixup_f32 v16, v16, v25, 1.0
	v_pk_mul_f32 v[12:13], v[0:1], v[0:1]
	v_mad_i64_i32 v[0:1], s[0:1], v50, s24, v[32:33]
	v_mul_f32_e32 v50, v16, v21
	v_lshlrev_b32_e32 v21, 16, v87
	v_mul_f32_e32 v25, 0xbfb8aa3b, v21
	v_fma_f32 v16, -v28, v41, 1.0
	v_exp_f32_e32 v25, v25
	v_fmac_f32_e32 v41, v16, v41
	v_div_scale_f32 v16, vcc, 1.0, v24, 1.0
	v_mul_f32_e32 v17, v16, v41
	v_fma_f32 v29, -v28, v17, v16
	v_fmac_f32_e32 v17, v29, v41
	v_add_f32_e32 v25, 1.0, v25
	v_fma_f32 v16, -v28, v17, v16
	v_div_scale_f32 v28, s[0:1], v25, v25, 1.0
	v_rcp_f32_e32 v29, v28
	v_div_fmas_f32 v16, v16, v41, v17
	v_div_fixup_f32 v16, v16, v24, 1.0
	v_lshlrev_b32_e32 v52, 16, v86
	v_mul_f32_e32 v41, v16, v20
	v_mul_f32_e32 v20, 0xbfb8aa3b, v52
	v_exp_f32_e32 v20, v20
	v_fma_f32 v16, -v28, v29, 1.0
	v_fmac_f32_e32 v29, v16, v29
	v_div_scale_f32 v16, vcc, 1.0, v25, 1.0
	v_mul_f32_e32 v17, v16, v29
	v_fma_f32 v24, -v28, v17, v16
	v_add_f32_e32 v20, 1.0, v20
	v_fmac_f32_e32 v17, v24, v29
	v_div_scale_f32 v24, s[0:1], v20, v20, 1.0
	v_fma_f32 v16, -v28, v17, v16
	v_rcp_f32_e32 v28, v24
	v_div_fmas_f32 v16, v16, v29, v17
	v_div_fixup_f32 v16, v16, v25, 1.0
	v_mul_f32_e32 v63, v16, v21
	v_fma_f32 v16, -v24, v28, 1.0
	v_fmac_f32_e32 v28, v16, v28
	v_div_scale_f32 v16, vcc, 1.0, v20, 1.0
	v_mul_f32_e32 v17, v16, v28
	v_fma_f32 v21, -v24, v17, v16
	v_fmac_f32_e32 v17, v21, v28
	v_fma_f32 v16, -v24, v17, v16
	v_div_fmas_f32 v16, v16, v28, v17
	v_div_fixup_f32 v64, v16, v20, 1.0
	v_mov_b32_e32 v16, v15
	v_mov_b32_e32 v17, v27
	v_pk_mul_f32 v[16:17], v[16:17], v[16:17]
	v_pk_fma_f32 v[36:37], v[30:31], v[30:31], v[36:37]
	v_mov_b32_e32 v20, v23
	v_mov_b32_e32 v21, v7
	v_mov_b32_e32 v28, v16
	v_mov_b32_e32 v29, v4
	v_pk_mul_f32 v[20:21], v[20:21], v[20:21]
	v_pk_add_f32 v[28:29], v[36:37], v[28:29] op_sel:[1,0] op_sel_hi:[0,1]
	v_mov_b32_e32 v4, v17
	v_mov_b32_e32 v24, v3
	v_mov_b32_e32 v25, v11
	v_pk_add_f32 v[4:5], v[28:29], v[4:5]
	v_mov_b32_e32 v16, v20
	v_mov_b32_e32 v17, v8
	v_pk_mul_f32 v[24:25], v[24:25], v[24:25]
	v_pk_add_f32 v[4:5], v[4:5], v[16:17]
	v_mov_b32_e32 v8, v21
	v_pk_add_f32 v[4:5], v[4:5], v[8:9]
	v_mov_b32_e32 v8, v24
	v_mov_b32_e32 v9, v12
	v_pk_add_f32 v[4:5], v[4:5], v[8:9]
	v_mov_b32_e32 v12, v25
	v_pk_add_f32 v[4:5], v[4:5], v[12:13]
	ds_bpermute_b32 v9, v60, v5
	ds_bpermute_b32 v8, v60, v4
	v_lshlrev_b32_e32 v13, 16, v85
	v_mul_f32_e32 v16, 0xbfb8aa3b, v13
	v_exp_f32_e32 v16, v16
	v_lshl_add_u64 v[0:1], v[0:1], 0, v[128:129]
	s_waitcnt lgkmcnt(0)
	v_pk_add_f32 v[4:5], v[4:5], v[8:9]
	ds_bpermute_b32 v9, v58, v5
	ds_bpermute_b32 v8, v58, v4
	v_add_f32_e32 v16, 1.0, v16
	v_div_scale_f32 v17, s[0:1], v16, v16, 1.0
	v_rcp_f32_e32 v20, v17
	s_waitcnt lgkmcnt(0)
	v_pk_add_f32 v[4:5], v[4:5], v[8:9]
	ds_bpermute_b32 v9, v47, v5
	ds_bpermute_b32 v8, v47, v4
	v_fma_f32 v21, -v17, v20, 1.0
	v_fmac_f32_e32 v20, v21, v20
	v_div_scale_f32 v21, vcc, 1.0, v16, 1.0
	s_waitcnt lgkmcnt(0)
	v_pk_add_f32 v[4:5], v[4:5], v[8:9]
	ds_bpermute_b32 v9, v46, v5
	ds_bpermute_b32 v8, v46, v4
	v_mul_f32_e32 v24, v21, v20
	v_mul_f32_e32 v12, v64, v52
	v_fma_f32 v25, -v17, v24, v21
	v_fmac_f32_e32 v24, v25, v20
	s_waitcnt lgkmcnt(0)
	v_pk_add_f32 v[4:5], v[4:5], v[8:9]
	v_fma_f32 v17, -v17, v24, v21
	v_pk_fma_f32 v[4:5], v[4:5], s[26:27], v[34:35] op_sel_hi:[1,0,0]
	v_readlane_b32 s70, v255, 7
	v_mul_f32_e32 v8, 0x4b800000, v5
	v_cmp_gt_f32_e64 s[0:1], s3, v5
	s_movk_i32 s84, 0xc00
	v_readlane_b32 s77, v255, 34
	v_cndmask_b32_e64 v5, v5, v8, s[0:1]
	v_rsq_f32_e32 v5, v5
	v_div_fmas_f32 v8, v17, v20, v24
	v_cmp_gt_f32_e32 vcc, s3, v4
	v_div_fixup_f32 v8, v8, v16, 1.0
	v_mul_f32_e32 v9, 0x45800000, v5
	v_cndmask_b32_e64 v5, v5, v9, s[0:1]
	v_mul_f32_e32 v9, v30, v5
	v_mul_f32_e32 v9, v43, v9
	v_mul_f32_e32 v9, v38, v9
	v_cvt_pk_bf16_f32 v9, v9, s0
	global_store_short v[0:1], v9, off
	v_mul_f32_e32 v9, v18, v5
	v_mul_f32_e32 v9, v62, v9
	v_mul_f32_e32 v9, v40, v9
	v_cvt_pk_bf16_f32 v9, v9, s0
	global_store_short v[0:1], v9, off offset:32
	v_mul_f32_e32 v9, v14, v5
	v_mul_f32_e32 v9, v61, v9
	v_mul_f32_e32 v9, v39, v9
	v_cvt_pk_bf16_f32 v9, v9, s0
	global_store_short v[0:1], v9, off offset:64
	v_mul_f32_e32 v9, v26, v5
	v_mul_f32_e32 v2, v2, v5
	v_mul_f32_e32 v9, v56, v9
	v_mul_f32_e32 v2, v44, v2
	v_mul_f32_e32 v9, v50, v9
	v_mul_f32_e32 v6, v6, v5
	v_mul_f32_e32 v2, v12, v2
	v_cvt_pk_bf16_f32 v9, v9, s0
	v_mul_f32_e32 v6, v45, v6
	v_cvt_pk_bf16_f32 v2, v2, s0
	global_store_short v[0:1], v9, off offset:96
	v_mul_f32_e32 v9, v22, v5
	v_mul_f32_e32 v6, v63, v6
	global_store_short v[0:1], v2, off offset:192
	v_mul_f32_e32 v2, v10, v5
	v_mul_f32_e32 v5, 0x4b800000, v4
	v_cvt_pk_bf16_f32 v6, v6, s0
	v_cndmask_b32_e32 v4, v4, v5, vcc
	v_lshlrev_b32_e32 v5, 16, v79
	global_store_short v[0:1], v6, off offset:160
	v_rsq_f32_e32 v4, v4
	v_mul_f32_e32 v6, 0xbfb8aa3b, v5
	v_mul_f32_e32 v8, v8, v13
	v_mul_f32_e32 v9, v54, v9
	v_mul_f32_e32 v2, v42, v2
	v_exp_f32_e32 v6, v6
	v_mul_f32_e32 v9, v41, v9
	v_mul_f32_e32 v2, v8, v2
	v_cvt_pk_bf16_f32 v9, v9, s0
	v_cvt_pk_bf16_f32 v2, v2, s0
	global_store_short v[0:1], v9, off offset:128
	global_store_short v[0:1], v2, off offset:224
	v_mul_f32_e32 v0, 0x45800000, v4
	v_cndmask_b32_e32 v2, v4, v0, vcc
	v_add_f32_e32 v4, 1.0, v6
	v_div_scale_f32 v6, s[0:1], v4, v4, 1.0
	v_rcp_f32_e32 v8, v6
	v_mul_f32_e32 v9, v31, v2
	v_mul_f32_e32 v9, v43, v9
	v_mad_i64_i32 v[0:1], s[0:1], v48, s24, v[32:33]
	v_fma_f32 v10, -v6, v8, 1.0
	v_fmac_f32_e32 v8, v10, v8
	v_div_scale_f32 v10, vcc, 1.0, v4, 1.0
	v_mul_f32_e32 v12, v10, v8
	v_fma_f32 v13, -v6, v12, v10
	v_fmac_f32_e32 v12, v13, v8
	v_fma_f32 v6, -v6, v12, v10
	v_div_fmas_f32 v6, v6, v8, v12
	v_div_fixup_f32 v4, v6, v4, 1.0
	v_mul_f32_e32 v4, v4, v5
	v_lshlrev_b32_e32 v5, 16, v78
	v_mul_f32_e32 v6, 0xbfb8aa3b, v5
	v_exp_f32_e32 v6, v6
	v_mul_f32_e32 v4, v4, v9
	v_cvt_pk_bf16_f32 v4, v4, s0
	v_lshl_add_u64 v[0:1], v[0:1], 0, v[128:129]
	v_add_f32_e32 v6, 1.0, v6
	v_div_scale_f32 v8, s[0:1], v6, v6, 1.0
	v_rcp_f32_e32 v9, v8
	global_store_short v[0:1], v4, off
	v_mul_f32_e32 v4, v19, v2
	v_mul_f32_e32 v4, v62, v4
	v_fma_f32 v10, -v8, v9, 1.0
	v_fmac_f32_e32 v9, v10, v9
	v_div_scale_f32 v10, vcc, 1.0, v6, 1.0
	v_mul_f32_e32 v12, v10, v9
	v_fma_f32 v13, -v8, v12, v10
	v_fmac_f32_e32 v12, v13, v9
	v_fma_f32 v8, -v8, v12, v10
	v_div_fmas_f32 v8, v8, v9, v12
	v_div_fixup_f32 v6, v8, v6, 1.0
	v_lshlrev_b32_e32 v8, 16, v59
	v_mul_f32_e32 v9, 0xbfb8aa3b, v8
	v_exp_f32_e32 v9, v9
	v_mul_f32_e32 v5, v6, v5
	v_mul_f32_e32 v4, v5, v4
	v_cvt_pk_bf16_f32 v4, v4, s0
	v_add_f32_e32 v5, 1.0, v9
	v_div_scale_f32 v6, s[0:1], v5, v5, 1.0
	v_rcp_f32_e32 v9, v6
	global_store_short v[0:1], v4, off offset:32
	v_mul_f32_e32 v4, v15, v2
	v_mul_f32_e32 v4, v61, v4
	v_fma_f32 v10, -v6, v9, 1.0
	v_fmac_f32_e32 v9, v10, v9
	v_div_scale_f32 v10, vcc, 1.0, v5, 1.0
	v_mul_f32_e32 v12, v10, v9
	v_fma_f32 v13, -v6, v12, v10
	v_fmac_f32_e32 v12, v13, v9
	v_fma_f32 v6, -v6, v12, v10
	v_div_fmas_f32 v6, v6, v9, v12
	v_div_fixup_f32 v5, v6, v5, 1.0
	v_lshlrev_b32_e32 v6, 16, v57
	v_mul_f32_e32 v9, 0xbfb8aa3b, v6
	v_exp_f32_e32 v9, v9
	v_mul_f32_e32 v5, v5, v8
	v_mul_f32_e32 v4, v5, v4
	v_cvt_pk_bf16_f32 v4, v4, s0
	v_add_f32_e32 v5, 1.0, v9
	v_div_scale_f32 v8, s[0:1], v5, v5, 1.0
	v_rcp_f32_e32 v9, v8
	global_store_short v[0:1], v4, off offset:64
	v_mul_f32_e32 v4, v27, v2
	v_mul_f32_e32 v4, v56, v4
	v_fma_f32 v10, -v8, v9, 1.0
	v_fmac_f32_e32 v9, v10, v9
	v_div_scale_f32 v10, vcc, 1.0, v5, 1.0
	v_mul_f32_e32 v12, v10, v9
	v_fma_f32 v13, -v8, v12, v10
	v_fmac_f32_e32 v12, v13, v9
	v_fma_f32 v8, -v8, v12, v10
	v_div_fmas_f32 v8, v8, v9, v12
	v_div_fixup_f32 v5, v8, v5, 1.0
	v_lshlrev_b32_e32 v8, 16, v55
	v_mul_f32_e32 v9, 0xbfb8aa3b, v8
	v_exp_f32_e32 v9, v9
	v_mul_f32_e32 v5, v5, v6
	v_mul_f32_e32 v4, v5, v4
	v_cvt_pk_bf16_f32 v4, v4, s0
	v_add_f32_e32 v5, 1.0, v9
	v_div_scale_f32 v6, s[0:1], v5, v5, 1.0
	v_rcp_f32_e32 v9, v6
	global_store_short v[0:1], v4, off offset:96
	v_mul_f32_e32 v4, v23, v2
	v_mul_f32_e32 v4, v54, v4
	v_fma_f32 v10, -v6, v9, 1.0
	v_fmac_f32_e32 v9, v10, v9
	v_div_scale_f32 v10, vcc, 1.0, v5, 1.0
	v_mul_f32_e32 v12, v10, v9
	v_fma_f32 v13, -v6, v12, v10
	v_fmac_f32_e32 v12, v13, v9
	v_fma_f32 v6, -v6, v12, v10
	v_div_fmas_f32 v6, v6, v9, v12
	v_div_fixup_f32 v5, v6, v5, 1.0
	v_lshlrev_b32_e32 v6, 16, v53
	v_mul_f32_e32 v9, 0xbfb8aa3b, v6
	v_exp_f32_e32 v9, v9
	v_mul_f32_e32 v5, v5, v8
	v_mul_f32_e32 v4, v5, v4
	v_cvt_pk_bf16_f32 v4, v4, s0
	v_add_f32_e32 v5, 1.0, v9
	v_div_scale_f32 v8, s[0:1], v5, v5, 1.0
	v_rcp_f32_e32 v9, v8
	global_store_short v[0:1], v4, off offset:128
	v_mul_f32_e32 v4, v7, v2
	v_mul_f32_e32 v4, v45, v4
	v_fma_f32 v7, -v8, v9, 1.0
	v_fmac_f32_e32 v9, v7, v9
	v_div_scale_f32 v7, vcc, 1.0, v5, 1.0
	v_mul_f32_e32 v10, v7, v9
	v_fma_f32 v12, -v8, v10, v7
	v_fmac_f32_e32 v10, v12, v9
	v_fma_f32 v7, -v8, v10, v7
	v_div_fmas_f32 v7, v7, v9, v10
	v_div_fixup_f32 v5, v7, v5, 1.0
	v_lshlrev_b32_e32 v7, 16, v51
	v_mul_f32_e32 v8, 0xbfb8aa3b, v7
	v_exp_f32_e32 v8, v8
	v_mul_f32_e32 v5, v5, v6
	v_mul_f32_e32 v4, v5, v4
	v_cvt_pk_bf16_f32 v4, v4, s0
	v_add_f32_e32 v5, 1.0, v8
	v_div_scale_f32 v6, s[0:1], v5, v5, 1.0
	v_rcp_f32_e32 v8, v6
	global_store_short v[0:1], v4, off offset:160
	v_mul_f32_e32 v3, v3, v2
	v_mul_f32_e32 v3, v44, v3
	v_fma_f32 v4, -v6, v8, 1.0
	v_fmac_f32_e32 v8, v4, v8
	v_div_scale_f32 v4, vcc, 1.0, v5, 1.0
	v_mul_f32_e32 v9, v4, v8
	v_fma_f32 v10, -v6, v9, v4
	v_fmac_f32_e32 v9, v10, v8
	v_fma_f32 v4, -v6, v9, v4
	v_div_fmas_f32 v4, v4, v8, v9
	v_div_fixup_f32 v4, v4, v5, 1.0
	v_lshlrev_b32_e32 v5, 16, v49
	v_mul_f32_e32 v6, 0xbfb8aa3b, v5
	v_exp_f32_e32 v6, v6
	v_mul_f32_e32 v4, v4, v7
	v_mul_f32_e32 v3, v4, v3
	v_cvt_pk_bf16_f32 v3, v3, s0
	v_add_f32_e32 v4, 1.0, v6
	v_div_scale_f32 v6, s[0:1], v4, v4, 1.0
	v_rcp_f32_e32 v7, v6
	global_store_short v[0:1], v3, off offset:192
	v_mul_f32_e32 v2, v11, v2
	v_mul_f32_e32 v2, v42, v2
	v_fma_f32 v3, -v6, v7, 1.0
	v_fmac_f32_e32 v7, v3, v7
	v_div_scale_f32 v3, vcc, 1.0, v4, 1.0
	v_mul_f32_e32 v8, v3, v7
	v_fma_f32 v9, -v6, v8, v3
	v_fmac_f32_e32 v8, v9, v7
	v_fma_f32 v3, -v6, v8, v3
	v_div_fmas_f32 v3, v3, v7, v8
	v_div_fixup_f32 v3, v3, v4, 1.0
	v_mul_f32_e32 v3, v3, v5
	v_mul_f32_e32 v2, v3, v2
	v_cvt_pk_bf16_f32 v2, v2, s0
	v_readlane_b32 s78, v255, 35
	v_readlane_b32 s79, v255, 36
	v_readlane_b32 s80, v255, 37
	v_readlane_b32 s81, v255, 38
	v_readlane_b32 s82, v255, 39
	v_readlane_b32 s83, v255, 40
	v_readlane_b32 s71, v255, 8
	s_movk_i32 s85, 0x1000
	s_movk_i32 s56, 0x3600
	global_store_short v[0:1], v2, off offset:224
	s_setprio 0

.LBB0_153:
	s_andn2_b64 vcc, exec, s[0:1]
	s_cbranch_vccnz .LBB0_135
	s_setprio 1
	v_mov_b32_e32 v7, v208
	s_ashr_i32 s24, s27, 2
	s_lshl_b32 s31, s24, 6
	v_ashrrev_i32_e32 v6, 2, v7
	v_and_b32_e32 v8, -16, v6
	v_lshrrev_b32_e32 v9, 2, v7
	v_add_u32_e32 v2, s31, v8
	v_and_b32_e32 v10, 12, v9
	v_or_b32_e32 v56, v2, v10
	v_mov_b64_e32 v[0:1], s[70:71]
	s_and_b32 s30, s27, 3
	v_mad_i64_i32 v[4:5], s[0:1], v56, s56, v[0:1]
	v_and_b32_e32 v54, 15, v7
	s_lshl_b32 s0, s30, 8
	s_mov_b32 s1, s29
	v_lshl_add_u64 v[4:5], v[4:5], 0, s[0:1]
	v_lshlrev_b32_e32 v58, 1, v54
	v_mov_b32_e32 v59, v129
	v_lshl_add_u64 v[4:5], v[4:5], 0, v[58:59]
	v_or_b32_e32 v52, 1, v56
	global_load_ushort v108, v[4:5], off offset:2048
	global_load_ushort v107, v[4:5], off offset:2080
	global_load_ushort v106, v[4:5], off offset:2112
	global_load_ushort v105, v[4:5], off offset:2144
	global_load_ushort v104, v[4:5], off offset:2176
	global_load_ushort v103, v[4:5], off offset:2208
	global_load_ushort v102, v[4:5], off offset:2240
	global_load_ushort v101, v[4:5], off offset:2272
	v_mad_i64_i32 v[4:5], s[36:37], v52, s56, v[0:1]
	v_lshl_add_u64 v[4:5], v[4:5], 0, s[0:1]
	v_lshl_add_u64 v[4:5], v[4:5], 0, v[58:59]
	v_or_b32_e32 v50, 2, v56
	global_load_ushort v100, v[4:5], off offset:2048
	global_load_ushort v99, v[4:5], off offset:2080
	global_load_ushort v98, v[4:5], off offset:2112
	global_load_ushort v97, v[4:5], off offset:2144
	global_load_ushort v96, v[4:5], off offset:2176
	global_load_ushort v95, v[4:5], off offset:2208
	global_load_ushort v94, v[4:5], off offset:2240
	global_load_ushort v93, v[4:5], off offset:2272
	v_mad_i64_i32 v[4:5], s[36:37], v50, s56, v[0:1]
	v_lshl_add_u64 v[4:5], v[4:5], 0, s[0:1]
	v_lshl_add_u64 v[4:5], v[4:5], 0, v[58:59]
	v_or_b32_e32 v48, 3, v56
	global_load_ushort v92, v[4:5], off offset:2048
	global_load_ushort v91, v[4:5], off offset:2080
	global_load_ushort v90, v[4:5], off offset:2112
	global_load_ushort v89, v[4:5], off offset:2144
	global_load_ushort v88, v[4:5], off offset:2176
	global_load_ushort v87, v[4:5], off offset:2208
	global_load_ushort v86, v[4:5], off offset:2240
	global_load_ushort v85, v[4:5], off offset:2272
	v_mad_i64_i32 v[4:5], s[36:37], v48, s56, v[0:1]
	v_lshl_add_u64 v[4:5], v[4:5], 0, s[0:1]
	v_lshl_add_u64 v[4:5], v[4:5], 0, v[58:59]
	s_lshl_b32 s28, s30, 7
	global_load_ushort v79, v[4:5], off offset:2048
	global_load_ushort v78, v[4:5], off offset:2080
	global_load_ushort v59, v[4:5], off offset:2112
	global_load_ushort v57, v[4:5], off offset:2144
	global_load_ushort v55, v[4:5], off offset:2176
	global_load_ushort v53, v[4:5], off offset:2208
	global_load_ushort v51, v[4:5], off offset:2240
	global_load_ushort v49, v[4:5], off offset:2272
	v_and_b32_e32 v11, 63, v7
	v_mad_i64_i32 v[4:5], s[36:37], v2, s56, v[0:1]
	v_lshl_add_u64 v[4:5], v[4:5], 0, s[28:29]
	v_lshlrev_b32_e32 v128, 1, v11
	v_lshl_add_u64 v[4:5], v[4:5], 0, v[128:129]
	global_load_ushort v109, v[4:5], off
	s_lshl_b32 s26, s30, 6
	v_readlane_b32 s25, v255, 48
	s_movk_i32 s38, 0x2000
	s_movk_i32 s39, 0x3000
	v_readlane_b32 s40, v252, 39
	v_readlane_b32 s54, v252, 53
	v_readlane_b32 s55, v252, 54
	v_readlane_b32 s41, v252, 40
	v_readlane_b32 s52, v252, 51
	v_readlane_b32 s53, v252, 52
	v_readlane_b32 s42, v252, 41
	v_readlane_b32 s43, v252, 42
	v_readlane_b32 s44, v252, 43
	v_readlane_b32 s45, v252, 44
	v_readlane_b32 s46, v252, 45
	v_readlane_b32 s47, v252, 46
	v_readlane_b32 s48, v252, 47
	v_readlane_b32 s49, v252, 48
	v_readlane_b32 s50, v252, 49
	v_readlane_b32 s51, v252, 50
	v_mul_u32_u24_e32 v19, 0x90, v54
	v_mov_b32_e32 v28, 0
	v_mov_b32_e32 v29, v28
	v_mov_b32_e32 v30, v28
	v_mov_b32_e32 v31, v28
	v_mov_b32_e32 v24, v28
	v_mov_b32_e32 v25, v28
	v_mov_b32_e32 v26, v28
	v_mov_b32_e32 v27, v28
	v_mov_b32_e32 v23, v28
	global_load_ushort v110, v[4:5], off offset:512
	v_or_b32_e32 v3, 1, v2
	v_mad_i64_i32 v[4:5], s[36:37], v3, s56, v[0:1]
	v_lshl_add_u64 v[4:5], v[4:5], 0, s[28:29]
	v_lshl_add_u64 v[4:5], v[4:5], 0, v[128:129]
	global_load_ushort v111, v[4:5], off
	global_load_ushort v112, v[4:5], off offset:512
	v_or_b32_e32 v3, 2, v2
	v_mad_i64_i32 v[4:5], s[36:37], v3, s56, v[0:1]
	v_lshl_add_u64 v[4:5], v[4:5], 0, s[28:29]
	v_lshl_add_u64 v[4:5], v[4:5], 0, v[128:129]
	global_load_ushort v113, v[4:5], off
	global_load_ushort v114, v[4:5], off offset:512
	v_or_b32_e32 v3, 3, v2
	v_mad_i64_i32 v[4:5], s[36:37], v3, s56, v[0:1]
	v_lshl_add_u64 v[4:5], v[4:5], 0, s[28:29]
	v_lshl_add_u64 v[4:5], v[4:5], 0, v[128:129]
	global_load_ushort v115, v[4:5], off
	global_load_ushort v116, v[4:5], off offset:512
	v_or_b32_e32 v3, 4, v2
	v_mad_i64_i32 v[4:5], s[36:37], v3, s56, v[0:1]
	v_lshl_add_u64 v[4:5], v[4:5], 0, s[28:29]
	v_lshl_add_u64 v[4:5], v[4:5], 0, v[128:129]
	global_load_ushort v117, v[4:5], off
	global_load_ushort v118, v[4:5], off offset:512
	v_or_b32_e32 v3, 5, v2
	v_mad_i64_i32 v[4:5], s[36:37], v3, s56, v[0:1]
	v_lshl_add_u64 v[4:5], v[4:5], 0, s[28:29]
	v_lshl_add_u64 v[4:5], v[4:5], 0, v[128:129]
	global_load_ushort v119, v[4:5], off
	global_load_ushort v120, v[4:5], off offset:512
	v_or_b32_e32 v3, 6, v2
	v_mad_i64_i32 v[4:5], s[36:37], v3, s56, v[0:1]
	v_lshl_add_u64 v[4:5], v[4:5], 0, s[28:29]
	v_lshl_add_u64 v[4:5], v[4:5], 0, v[128:129]
	global_load_ushort v121, v[4:5], off
	global_load_ushort v122, v[4:5], off offset:512
	v_or_b32_e32 v3, 7, v2
	v_mad_i64_i32 v[4:5], s[36:37], v3, s56, v[0:1]
	v_lshl_add_u64 v[4:5], v[4:5], 0, s[28:29]
	v_lshl_add_u64 v[4:5], v[4:5], 0, v[128:129]
	global_load_ushort v123, v[4:5], off
	global_load_ushort v124, v[4:5], off offset:512
	v_or_b32_e32 v3, 8, v2
	v_mad_i64_i32 v[4:5], s[36:37], v3, s56, v[0:1]
	v_lshl_add_u64 v[4:5], v[4:5], 0, s[28:29]
	v_lshl_add_u64 v[4:5], v[4:5], 0, v[128:129]
	global_load_ushort v125, v[4:5], off
	global_load_ushort v126, v[4:5], off offset:512
	v_or_b32_e32 v3, 9, v2
	v_mad_i64_i32 v[4:5], s[36:37], v3, s56, v[0:1]
	v_lshl_add_u64 v[4:5], v[4:5], 0, s[28:29]
	v_lshl_add_u64 v[4:5], v[4:5], 0, v[128:129]
	global_load_ushort v127, v[4:5], off
	global_load_ushort v133, v[4:5], off offset:512
	v_or_b32_e32 v3, 10, v2
	v_mad_i64_i32 v[4:5], s[36:37], v3, s56, v[0:1]
	v_lshl_add_u64 v[4:5], v[4:5], 0, s[28:29]
	v_lshl_add_u64 v[4:5], v[4:5], 0, v[128:129]
	global_load_ushort v134, v[4:5], off
	global_load_ushort v135, v[4:5], off offset:512
	v_or_b32_e32 v3, 11, v2
	v_mad_i64_i32 v[4:5], s[36:37], v3, s56, v[0:1]
	v_lshl_add_u64 v[4:5], v[4:5], 0, s[28:29]
	v_lshl_add_u64 v[4:5], v[4:5], 0, v[128:129]
	global_load_ushort v136, v[4:5], off
	global_load_ushort v137, v[4:5], off offset:512
	v_or_b32_e32 v3, 12, v2
	v_mad_i64_i32 v[4:5], s[36:37], v3, s56, v[0:1]
	v_lshl_add_u64 v[4:5], v[4:5], 0, s[28:29]
	v_lshl_add_u64 v[4:5], v[4:5], 0, v[128:129]
	global_load_ushort v138, v[4:5], off
	global_load_ushort v139, v[4:5], off offset:512
	v_or_b32_e32 v3, 13, v2
	v_mad_i64_i32 v[4:5], s[36:37], v3, s56, v[0:1]
	v_lshl_add_u64 v[4:5], v[4:5], 0, s[28:29]
	v_lshl_add_u64 v[4:5], v[4:5], 0, v[128:129]
	global_load_ushort v140, v[4:5], off
	global_load_ushort v141, v[4:5], off offset:512
	v_or_b32_e32 v3, 14, v2
	v_mad_i64_i32 v[4:5], s[36:37], v3, s56, v[0:1]
	v_lshl_add_u64 v[4:5], v[4:5], 0, s[28:29]
	v_lshl_add_u64 v[4:5], v[4:5], 0, v[128:129]
	global_load_ushort v142, v[4:5], off
	v_or_b32_e32 v2, 15, v2
	global_load_ushort v143, v[4:5], off offset:512
	v_mad_i64_i32 v[2:3], s[36:37], v2, s56, v[0:1]
	v_lshl_add_u64 v[2:3], v[2:3], 0, s[28:29]
	v_lshl_add_u64 v[2:3], v[2:3], 0, v[128:129]
	global_load_ushort v4, v[2:3], off
	s_add_u32 s36, s25, s0
	global_load_ushort v2, v[2:3], off offset:512
	v_readlane_b32 s25, v255, 49
	s_addc_u32 s37, s25, 0
	v_mov_b32_e32 v3, v129
	s_mov_b32 s25, 0
	s_waitcnt vmcnt(0)
	v_lshlrev_b32_e32 v109, 16, v109
	v_mul_f32_e32 v109, 0x3e000000, v109
	v_lshlrev_b32_e32 v110, 16, v110
	v_lshlrev_b32_e32 v111, 16, v111
	v_mul_f32_e32 v111, 0x3e000000, v111
	v_lshlrev_b32_e32 v112, 16, v112
	v_lshlrev_b32_e32 v113, 16, v113
	v_mul_f32_e32 v113, 0x3e000000, v113
	v_lshlrev_b32_e32 v114, 16, v114
	v_lshlrev_b32_e32 v115, 16, v115
	v_mul_f32_e32 v115, 0x3e000000, v115
	v_lshlrev_b32_e32 v116, 16, v116
	v_lshlrev_b32_e32 v117, 16, v117
	v_mul_f32_e32 v117, 0x3e000000, v117
	v_lshlrev_b32_e32 v118, 16, v118
	v_lshlrev_b32_e32 v119, 16, v119
	v_mul_f32_e32 v119, 0x3e000000, v119
	v_lshlrev_b32_e32 v120, 16, v120
	v_lshlrev_b32_e32 v121, 16, v121
	v_mul_f32_e32 v121, 0x3e000000, v121
	v_lshlrev_b32_e32 v122, 16, v122
	v_lshlrev_b32_e32 v123, 16, v123
	v_mul_f32_e32 v123, 0x3e000000, v123
	v_lshlrev_b32_e32 v124, 16, v124
	v_lshlrev_b32_e32 v125, 16, v125
	v_mul_f32_e32 v125, 0x3e000000, v125
	v_lshlrev_b32_e32 v126, 16, v126
	v_lshlrev_b32_e32 v127, 16, v127
	v_mul_f32_e32 v127, 0x3e000000, v127
	v_lshlrev_b32_e32 v133, 16, v133
	v_lshlrev_b32_e32 v134, 16, v134
	v_mul_f32_e32 v134, 0x3e000000, v134
	v_lshlrev_b32_e32 v135, 16, v135
	v_lshlrev_b32_e32 v136, 16, v136
	v_mul_f32_e32 v136, 0x3e000000, v136
	v_lshlrev_b32_e32 v137, 16, v137
	v_lshlrev_b32_e32 v138, 16, v138
	v_mul_f32_e32 v138, 0x3e000000, v138
	v_lshlrev_b32_e32 v139, 16, v139
	v_lshlrev_b32_e32 v140, 16, v140
	v_mul_f32_e32 v140, 0x3e000000, v140
	v_lshlrev_b32_e32 v141, 16, v141
	v_lshlrev_b32_e32 v142, 16, v142
	v_mul_f32_e32 v142, 0x3e000000, v142
	v_lshlrev_b32_e32 v143, 16, v143
	v_lshlrev_b32_e32 v4, 16, v4
	v_mul_f32_e32 v144, 0x3e000000, v4
	v_lshlrev_b32_e32 v145, 16, v2
	v_mov_b32_e32 v2, v208
	s_nop 0
	v_and_b32_e32 v14, 63, v2
	v_lshlrev_b32_e32 v2, 2, v14
	v_lshl_add_u64 v[4:5], s[36:37], 0, v[2:3]
	global_load_dword v146, v2, s[36:37]
	global_load_dword v147, v2, s[36:37] offset:1024
	global_load_dword v148, v2, s[36:37] offset:2048
	global_load_dword v149, v2, s[36:37] offset:3072
	v_add_co_u32_e32 v2, vcc, s85, v4
	v_readlane_b32 s36, v255, 44
	s_nop 0
	v_addc_co_u32_e32 v3, vcc, 0, v5, vcc
	v_add_co_u32_e32 v12, vcc, s38, v4
	s_or_b32 s36, s26, s36
	s_nop 0
	v_addc_co_u32_e32 v13, vcc, 0, v5, vcc
	global_load_dword v150, v[12:13], off offset:-4096
	global_load_dword v151, v[2:3], off offset:1024
	global_load_dword v152, v[2:3], off offset:2048
	global_load_dword v153, v[2:3], off offset:3072
	global_load_dword v154, v[12:13], off
	global_load_dword v155, v[12:13], off offset:1024
	global_load_dword v156, v[12:13], off offset:2048
	global_load_dword v157, v[12:13], off offset:3072
	v_add_co_u32_e32 v2, vcc, s39, v4
	v_readlane_b32 s37, v255, 51
	s_nop 0
	v_addc_co_u32_e32 v3, vcc, 0, v5, vcc
	global_load_dword v158, v[2:3], off
	global_load_dword v159, v[2:3], off offset:1024
	global_load_dword v160, v[2:3], off offset:2048
	global_load_dword v161, v[2:3], off offset:3072
	v_or_b32_e32 v2, s36, v14
	v_ashrrev_i32_e32 v3, 31, v2
	v_lshl_add_u64 v[2:3], v[2:3], 2, s[54:55]
	global_load_dword v162, v[2:3], off
	v_mov_b32_e32 v2, v208
	v_readlane_b32 s36, v255, 50
	s_add_u32 s36, s36, s0
	v_and_b32_e32 v14, 63, v2
	s_addc_u32 s37, s37, 0
	v_lshlrev_b32_e32 v2, 2, v14
	v_mov_b32_e32 v3, v129
	v_lshl_add_u64 v[4:5], s[36:37], 0, v[2:3]
	global_load_dword v163, v2, s[36:37]
	global_load_dword v164, v2, s[36:37] offset:1024
	global_load_dword v165, v2, s[36:37] offset:2048
	global_load_dword v166, v2, s[36:37] offset:3072
	v_add_co_u32_e32 v2, vcc, s85, v4
	v_readlane_b32 s36, v255, 45
	s_nop 0
	v_addc_co_u32_e32 v3, vcc, 0, v5, vcc
	v_add_co_u32_e32 v12, vcc, s38, v4
	s_or_b32 s26, s26, s36
	s_nop 0
	v_addc_co_u32_e32 v13, vcc, 0, v5, vcc
	global_load_dword v167, v[12:13], off offset:-4096
	global_load_dword v168, v[2:3], off offset:1024
	global_load_dword v169, v[2:3], off offset:2048
	global_load_dword v170, v[2:3], off offset:3072
	global_load_dword v171, v[12:13], off
	global_load_dword v172, v[12:13], off offset:1024
	global_load_dword v173, v[12:13], off offset:2048
	global_load_dword v174, v[12:13], off offset:3072
	v_add_co_u32_e32 v2, vcc, s39, v4
	v_mov_b32_e32 v13, v208
	s_nop 0
	v_addc_co_u32_e32 v3, vcc, 0, v5, vcc
	global_load_dword v175, v[2:3], off
	global_load_dword v176, v[2:3], off offset:1024
	global_load_dword v177, v[2:3], off offset:2048
	global_load_dword v178, v[2:3], off offset:3072
	v_or_b32_e32 v2, s26, v14
	v_ashrrev_i32_e32 v3, 31, v2
	v_lshl_add_u64 v[2:3], v[2:3], 2, s[54:55]
	global_load_dword v179, v[2:3], off
	v_mov_b32_e32 v5, v129
	v_ashrrev_i32_e32 v2, 5, v13
	v_and_b32_e32 v4, 31, v13
	v_add_u32_e32 v2, s31, v2
	v_mad_i64_i32 v[2:3], s[36:37], v2, s56, v[0:1]
	v_lshlrev_b32_e32 v4, 1, v4
	v_lshl_add_u64 v[2:3], v[2:3], 0, v[4:5]
	global_load_ushort v232, v[2:3], off offset:3072
	v_add_u32_e32 v16, 0x100, v13
	v_lshlrev_b32_e32 v14, 2, v13
	v_mov_b32_e32 v84, v14
	v_add_u32_e32 v17, 0x200, v13
	v_add_u32_e32 v18, 0x300, v13
	s_movk_i32 s26, 0x110
	v_ashrrev_i32_e32 v2, 5, v16
	v_add_u32_e32 v2, s31, v2
	v_mad_i64_i32 v[2:3], s[36:37], v2, s56, v[0:1]
	v_lshl_add_u64 v[2:3], v[2:3], 0, v[4:5]
	global_load_ushort v233, v[2:3], off offset:3072
	v_ashrrev_i32_e32 v2, 5, v17
	v_add_u32_e32 v2, s31, v2
	v_mad_i64_i32 v[2:3], s[36:37], v2, s56, v[0:1]
	v_lshl_add_u64 v[2:3], v[2:3], 0, v[4:5]
	global_load_ushort v234, v[2:3], off offset:3072
	v_ashrrev_i32_e32 v2, 5, v18
	v_add_u32_e32 v2, s31, v2
	v_mad_i64_i32 v[2:3], s[36:37], v2, s56, v[0:1]
	v_lshl_add_u64 v[2:3], v[2:3], 0, v[4:5]
	global_load_ushort v235, v[2:3], off offset:3072
	v_add_u32_e32 v2, 0x400, v13
	v_ashrrev_i32_e32 v2, 5, v2
	v_add_u32_e32 v2, s31, v2
	v_mad_i64_i32 v[2:3], s[36:37], v2, s56, v[0:1]
	v_lshl_add_u64 v[2:3], v[2:3], 0, v[4:5]
	global_load_ushort v236, v[2:3], off offset:3072
	v_add_u32_e32 v2, 0x500, v13
	v_ashrrev_i32_e32 v2, 5, v2
	v_add_u32_e32 v2, s31, v2
	v_mad_i64_i32 v[2:3], s[36:37], v2, s56, v[0:1]
	v_lshl_add_u64 v[2:3], v[2:3], 0, v[4:5]
	global_load_ushort v237, v[2:3], off offset:3072
	v_add_u32_e32 v2, 0x600, v13
	v_ashrrev_i32_e32 v2, 5, v2
	v_add_u32_e32 v2, s31, v2
	v_mad_i64_i32 v[2:3], s[36:37], v2, s56, v[0:1]
	v_lshl_add_u64 v[2:3], v[2:3], 0, v[4:5]
	global_load_ushort v238, v[2:3], off offset:3072
	v_add_u32_e32 v2, 0x700, v13
	v_ashrrev_i32_e32 v2, 5, v2
	v_add_u32_e32 v2, s31, v2
	v_mad_i64_i32 v[2:3], s[36:37], v2, s56, v[0:1]
	v_lshl_add_u64 v[2:3], v[2:3], 0, v[4:5]
	global_load_ushort v239, v[2:3], off offset:3072
	v_ashrrev_i32_e32 v4, 4, v13
	v_lshlrev_b32_e32 v2, 4, v13
	v_and_b32_e32 v12, 0xf0, v2
	v_add_u32_e32 v2, s31, v4
	v_mad_i64_i32 v[2:3], s[36:37], v2, s56, v[0:1]
	v_lshl_add_u64 v[2:3], v[2:3], 0, s[0:1]
	v_mov_b32_e32 v13, v129
	v_lshl_add_u64 v[2:3], v[2:3], 0, v[12:13]
	v_mad_u64_u32 v[14:15], s[36:37], v4, s26, v[12:13]
	v_mov_b32_e32 v248, v14
	global_load_dwordx4 v[240:243], v[2:3], off offset:1024
	v_ashrrev_i32_e32 v4, 4, v16
	v_add_u32_e32 v2, s31, v4
	v_mad_i64_i32 v[2:3], s[36:37], v2, s56, v[0:1]
	v_lshl_add_u64 v[2:3], v[2:3], 0, s[0:1]
	v_lshl_add_u64 v[2:3], v[2:3], 0, v[12:13]
	v_mad_u64_u32 v[14:15], s[36:37], v4, s26, v[12:13]
	v_mov_b32_e32 v249, v14
	global_load_dwordx4 v[244:247], v[2:3], off offset:1024
	v_ashrrev_i32_e32 v4, 4, v17
	v_add_u32_e32 v2, s31, v4
	v_mad_i64_i32 v[2:3], s[36:37], v2, s56, v[0:1]
	v_lshl_add_u64 v[2:3], v[2:3], 0, s[0:1]
	v_lshl_add_u64 v[2:3], v[2:3], 0, v[12:13]
	v_mad_u64_u32 v[14:15], s[36:37], v4, s26, v[12:13]
	v_mov_b32_e32 v220, v14
	global_load_dwordx4 v[216:219], v[2:3], off offset:1024
	v_mul_lo_u32 v15, v8, s33
	v_ashrrev_i32_e32 v2, 4, v18
	v_add_u32_e32 v3, s31, v2
	v_mad_i64_i32 v[0:1], s[36:37], v3, s56, v[0:1]
	v_lshl_add_u64 v[0:1], v[0:1], 0, s[0:1]
	v_lshl_add_u64 v[0:1], v[0:1], 0, v[12:13]
	v_mad_u64_u32 v[4:5], s[0:1], v2, s26, v[12:13]
	global_load_dwordx4 v[80:83], v[0:1], off offset:1024
	s_movk_i32 s26, 0x90
	s_lshl_b32 s0, s24, 3
	s_lshl_b32 s1, s30, 1
	v_mul_lo_u32 v16, v8, s26
	v_or_b32_e32 v12, 48, v54
	s_or_b32 s24, s1, s0
	v_readlane_b32 s0, v253, 25
	v_lshlrev_b32_e32 v22, 1, v12
	v_readlane_b32 s1, v253, 26
	s_mov_b64 s[30:31], -1
	s_waitcnt vmcnt(0)
	v_lshlrev_b32_e32 v232, 16, v232
	v_lshlrev_b32_e32 v233, 16, v233
	ds_write2st64_b32 v84, v232, v233 offset0:69 offset1:73
	v_lshlrev_b32_e32 v234, 16, v234
	v_lshlrev_b32_e32 v235, 16, v235
	ds_write2st64_b32 v84, v234, v235 offset0:77 offset1:81
	v_lshlrev_b32_e32 v236, 16, v236
	v_lshlrev_b32_e32 v237, 16, v237
	ds_write2st64_b32 v84, v236, v237 offset0:85 offset1:89
	v_lshlrev_b32_e32 v238, 16, v238
	v_lshlrev_b32_e32 v239, 16, v239
	ds_write2st64_b32 v84, v238, v239 offset0:93 offset1:97
	ds_write_b128 v248, v[240:243] offset:44288
	ds_write_b128 v249, v[244:247] offset:44288
	ds_write_b128 v220, v[216:219] offset:44288
	ds_write_b128 v4, v[80:83] offset:44288
	v_lshrrev_b32_e32 v2, 1, v7
	v_and_b32_e32 v13, 24, v2
	v_bfi_b32 v0, -16, v6, v7
	v_and_or_b32 v2, v9, 3, v13
	v_mul_lo_u32 v5, v0, s26
	v_or_b32_e32 v0, v8, v10
	v_lshlrev_b32_e32 v4, 3, v7
	v_mul_u32_u24_e32 v9, 0x110, v2
	v_or_b32_e32 v2, 15, v6
	v_or_b32_e32 v8, 16, v54
	v_or_b32_e32 v10, 32, v54
	v_lshlrev_b32_e32 v1, 2, v11
	v_and_b32_e32 v11, 48, v7
	v_and_b32_e32 v7, 24, v4
	v_mul_lo_u32 v17, v2, s33
	v_mul_lo_u32 v18, v2, s26
	v_cmp_ge_i32_e64 s[36:37], v54, v0
	v_cmp_le_i32_e64 s[38:39], v54, v0
	v_mul_lo_u32 v180, v0, s26
	v_or_b32_e32 v2, 1, v0
	v_cmp_gt_i32_e64 s[40:41], v54, v0
	v_or_b32_e32 v4, 2, v0
	v_or_b32_e32 v6, 3, v0
	v_cmp_ge_i32_e64 s[52:53], v8, v0
	v_cmp_le_i32_e64 s[54:55], v8, v0
	v_cmp_gt_i32_e64 s[56:57], v8, v0
	v_cmp_ge_i32_e64 s[68:69], v10, v0
	v_cmp_le_i32_e64 s[70:71], v10, v0
	v_cmp_gt_i32_e64 s[72:73], v10, v0
	v_cmp_ge_i32_e64 s[84:85], v12, v0
	v_cmp_le_i32_e64 s[86:87], v12, v0
	v_cmp_gt_i32_e64 s[88:89], v12, v0
	v_lshlrev_b32_e32 v0, 6, v54
	v_sub_u32_e32 v3, v1, v128
	v_cmp_le_i32_e64 s[42:43], v54, v2
	v_cmp_ge_i32_e64 s[44:45], v54, v4
	v_cmp_le_i32_e64 s[46:47], v54, v4
	v_cmp_ge_i32_e64 s[48:49], v54, v6
	v_cmp_le_i32_e64 s[50:51], v54, v6
	v_lshlrev_b32_e32 v20, 1, v8
	v_cmp_le_i32_e64 s[58:59], v8, v2
	v_cmp_ge_i32_e64 s[60:61], v8, v4
	v_cmp_le_i32_e64 s[62:63], v8, v4
	v_cmp_ge_i32_e64 s[64:65], v8, v6
	v_cmp_le_i32_e64 s[66:67], v8, v6
	v_lshlrev_b32_e32 v21, 1, v10
	v_cmp_le_i32_e64 s[74:75], v10, v2
	v_cmp_ge_i32_e64 s[76:77], v10, v4
	v_cmp_le_i32_e64 s[78:79], v10, v4
	v_cmp_ge_i32_e64 s[80:81], v10, v6
	v_cmp_le_i32_e64 s[82:83], v10, v6
	v_cmp_le_i32_e64 s[90:91], v12, v2
	v_cmp_ge_i32_e64 s[92:93], v12, v4
	v_cmp_le_i32_e64 s[94:95], v12, v4
	v_cmp_ge_i32_e64 s[96:97], v12, v6
	v_cmp_le_i32_e64 s[98:99], v12, v6
	v_lshlrev_b32_e32 v2, 6, v8
	v_lshlrev_b32_e32 v4, 6, v10
	v_lshlrev_b32_e32 v6, 6, v12
	v_or_b32_e32 v8, 0x1000, v0
	v_or_b32_e32 v10, 0x1400, v0
	v_or_b32_e32 v12, 0x1800, v0
	v_or_b32_e32 v14, 0x1c00, v0
	v_lshlrev_b32_e32 v128, 1, v13
	v_lshl_add_u64 v[60:61], s[0:1], 0, v[128:129]
	v_add_u32_e32 v181, v1, v15
	v_add_u32_e32 v182, v3, v16
	v_add_u32_e32 v183, v1, v17
	v_add_u32_e32 v184, v3, v18
	v_add_u32_e32 v185, v5, v11
	v_add_u32_e32 v186, v11, v19
	v_add_u32_e32 v187, v20, v180
	v_add_u32_e32 v188, v21, v180
	v_add_u32_e32 v189, v22, v180
	v_add_u32_e32 v190, v7, v9
	v_lshlrev_b32_e32 v128, 1, v0
	v_lshlrev_b32_e32 v62, 1, v2
	v_lshlrev_b32_e32 v64, 1, v4
	v_lshlrev_b32_e32 v66, 1, v6
	v_lshlrev_b32_e32 v68, 1, v8
	v_lshlrev_b32_e32 v70, 1, v10
	v_lshlrev_b32_e32 v72, 1, v12
	v_lshlrev_b32_e32 v74, 1, v14
	v_mov_b32_e32 v16, v28
	v_mov_b32_e32 v17, v28
	v_mov_b32_e32 v18, v28
	v_mov_b32_e32 v19, v28
	v_mov_b32_e32 v12, v28
	v_mov_b32_e32 v13, v28
	v_mov_b32_e32 v14, v28
	v_mov_b32_e32 v15, v28
	v_mov_b32_e32 v20, v28
	v_mov_b32_e32 v21, v28
	v_mov_b32_e32 v22, v28
	v_mov_b32_e32 v4, v28
	v_mov_b32_e32 v5, v28
	v_mov_b32_e32 v6, v28
	v_mov_b32_e32 v7, v28
	v_mov_b32_e32 v0, v28
	v_mov_b32_e32 v1, v28
	v_mov_b32_e32 v2, v28
	v_mov_b32_e32 v3, v28
	v_mov_b32_e32 v8, v28
	v_mov_b32_e32 v9, v28
	v_mov_b32_e32 v10, v28
	v_mov_b32_e32 v11, v28
	s_waitcnt lgkmcnt(0)
	s_barrier
	s_branch .LBB0_156
